# hgA and hgC: the two lower-bound-logit loads now issue before the next-chunk prefetch loads, and their wait is a counted vmcnt (4 / 22) instead of a drain that also waited for the prefetch; on top of
# speedup vs baseline: 1.0106x; 1.0106x over previous
; DI void hg_gates(const LAS unsigned char* rawf, const float* lbl, int part, int hh, int d, float (&G)[16], float (&kk)[16]) {
;     const float l0 = lbl[hh * 128 + d], l1 = lbl[1024 + hh * 128 + d]; const float lb = __builtin_amdgcn_rcpf(1.f + __expf(l1 - l0));
; DI void hg_phase_a(const P& p, const bf16_t* PROJ, float* UT, float* DEC, LAS unsigned char* L) {
;     ...
;     for (int ch = blockIdx.x; ch < 2048; ch += gridDim.x) {
;         const int bh = ch >> 6, hh = bh & 7;
;         __syncthreads();
;         hg_raw_store(rawf, tid, rf); hg_raw_store(rawv, tid, rv);
;         if (ch + (int)gridDim.x < 2048) { hg_raw_load(PROJ, ch + gridDim.x, 4096, roff, rf); hg_raw_load(PROJ, ch + gridDim.x, 5120, roff, rv); }
.LBB0_285:
	s_add_i32 s34, s18, s86
	s_cmpk_gt_i32 s34, 0x7ff
	s_cselect_b64 s[16:17], -1, 0
	s_and_b64 vcc, exec, s[16:17]
	s_waitcnt lgkmcnt(0)
	s_barrier
	s_waitcnt vmcnt(3)
	ds_write_b128 v57, v[32:35] offset:40960
	s_waitcnt vmcnt(1)
	ds_write_b128 v57, v[40:43] offset:49664
	ds_write_b128 v57, v[36:39] offset:58368
	s_waitcnt vmcnt(0)
	ds_write_b128 v58, v[44:47] offset:8704
	s_and_b32 s19, s24, 0x380
	v_or_b32_e32 v92, s19, v56
	v_lshlrev_b32_e32 v92, 2, v92
	s_add_u32 s100, s14, 0x1000
	s_addc_u32 s101, s15, 0
	global_load_dword v90, v92, s[14:15]
	global_load_dword v91, v92, s[100:101]
	s_cbranch_vccnz .Lhga_nopf
	s_ashr_i32 s20, s34, 9
	s_ashr_i32 s21, s20, 31
	s_lshl_b64 s[20:21], s[20:21], 12
	s_and_b32 s19, s27, 0xfc0
	s_or_b32 s19, s20, s19
	s_mul_i32 s20, s21, 0x3800
	s_mul_hi_u32 s21, s19, 0x3800
	s_add_i32 s21, s21, s20
	s_mulk_i32 s19, 0x3800
	s_add_u32 s19, s22, s19
	s_addc_u32 s21, s23, s21
	s_add_i32 s20, s26, s24
	s_and_b32 s20, s20, 0x380
	s_lshl_b32 s20, s20, 1
	s_add_u32 s20, s19, s20
	s_addc_u32 s21, s21, 0
	v_lshl_add_u64 v[0:1], v[50:51], 1, s[20:21]
	v_add_co_u32_e32 v2, vcc, 0x2000, v0
	s_nop 1
	v_addc_co_u32_e32 v3, vcc, 0, v1, vcc
	v_add_co_u32_e32 v0, vcc, 0x72000, v0
	s_nop 1
	v_addc_co_u32_e32 v1, vcc, 0, v1, vcc
	global_load_dwordx4 v[32:35], v[2:3], off
	global_load_dwordx4 v[36:39], v[2:3], off offset:2048
	global_load_dwordx4 v[40:43], v[0:1], off
	global_load_dwordx4 v[44:47], v[0:1], off offset:2048
	s_branch .LBB0_287

; #define LAS __attribute__((address_space(3)))
; DI float bf2f(unsigned v) { return __uint_as_float(v << 16); }
; DI void hg_gates(const LAS unsigned char* rawf, const float* lbl, int part, int hh, int d, float (&G)[16], float (&kk)[16]) {
;     const float l0 = lbl[hh * 128 + d], l1 = lbl[1024 + hh * 128 + d]; const float lb = __builtin_amdgcn_rcpf(1.f + __expf(l1 - l0));
;     float run = 0.f;
; #pragma unroll
;     for (int i = 0; i < 16; ++i) {
;         const float fl = bf2f(*(const LAS bf16_t*)(rawf + (16 * part + i) * 272 + d * 2));
;         const float sig = __builtin_amdgcn_rcpf(1.f + __expf(-fl)); const float f = lb + (1.f - lb) * sig;
;         kk[i] = (1.f - lb) * (1.f - sig); run += __builtin_amdgcn_logf(f) * 0.69314718056f; G[i] = run;
;     }
; }
; DI void hg_phase_a(const P& p, const bf16_t* PROJ, float* UT, float* DEC, LAS unsigned char* L) {
;     ...
;         hg_gates(rawf, p.lb_logits, part, hh, d, G, kk);
;         psum[part * 128 + d] = G[15];
;         { u32x4 a, c; hg_col16(rawv, part, d, a, c); *(LAS u32x4*)(vT + d * 144 + part * 32) = a; *(LAS u32x4*)(vT + d * 144 + part * 32 + 16) = c; }
.LBB0_287:
	s_and_b32 s19, s24, 0x380
	v_or_b32_e32 v0, s19, v56
	v_lshlrev_b32_e32 v48, 2, v0
	v_lshl_add_u64 v[0:1], s[14:15], 0, v[48:49]
	v_add_co_u32_e32 v0, vcc, 0x1000, v0
	s_waitcnt lgkmcnt(0)
	s_nop 0
	v_addc_co_u32_e32 v1, vcc, 0, v1, vcc
	s_barrier
	s_ashr_i32 s19, s18, 31
	ds_read_u16 v1, v63 offset:40960
	ds_read_u16 v3, v63 offset:41232
	ds_read_u16 v4, v63 offset:41504
	ds_read_u16 v5, v63 offset:41776
	ds_read_u16 v6, v63 offset:42048
	ds_read_u16 v7, v63 offset:42320
	ds_read_u16 v8, v63 offset:42592
	ds_read_u16 v9, v63 offset:42864
	ds_read_u16 v10, v63 offset:43136
	ds_read_u16 v11, v63 offset:43408
	ds_read_u16 v12, v63 offset:43680
	ds_read_u16 v21, v63 offset:43952
	ds_read_u16 v22, v63 offset:44224
	ds_read_u16 v23, v63 offset:44496
	ds_read_u16 v24, v63 offset:44768
	ds_read_u16 v25, v63 offset:45040
	s_waitcnt lgkmcnt(14)
	v_lshlrev_b32_e32 v1, 16, v1
	s_waitcnt lgkmcnt(7)
	v_lshlrev_b32_e32 v10, 16, v10
	v_mul_f32_e32 v1, 0xbfb8aa3b, v1
	v_mul_f32_e32 v10, 0xbfb8aa3b, v10
	v_exp_f32_e32 v1, v1
	v_exp_f32_e32 v10, v10
	v_lshlrev_b32_e32 v3, 16, v3
	v_lshlrev_b32_e32 v4, 16, v4
	v_add_f32_e32 v1, 1.0, v1
	v_add_f32_e32 v18, 1.0, v10
	v_rcp_f32_e32 v10, v1
	s_waitcnt lgkmcnt(6)
	v_lshlrev_b32_e32 v11, 16, v11
	v_mul_f32_e32 v3, 0xbfb8aa3b, v3
	v_lshlrev_b32_e32 v5, 16, v5
	v_mul_f32_e32 v4, 0xbfb8aa3b, v4
	v_mul_f32_e32 v11, 0xbfb8aa3b, v11
	v_exp_f32_e32 v3, v3
	v_lshlrev_b32_e32 v6, 16, v6
	v_mul_f32_e32 v5, 0xbfb8aa3b, v5
	v_exp_f32_e32 v4, v4
	v_exp_f32_e32 v11, v11
	v_lshlrev_b32_e32 v7, 16, v7
	v_mul_f32_e32 v6, 0xbfb8aa3b, v6
	v_exp_f32_e32 v5, v5
	v_lshlrev_b32_e32 v8, 16, v8
	v_mul_f32_e32 v7, 0xbfb8aa3b, v7
	v_exp_f32_e32 v6, v6
	v_lshlrev_b32_e32 v9, 16, v9
	s_waitcnt lgkmcnt(5)
	v_lshlrev_b32_e32 v20, 16, v12
	v_mul_f32_e32 v8, 0xbfb8aa3b, v8
	v_exp_f32_e32 v7, v7
	v_add_f32_e32 v3, 1.0, v3
	v_mul_f32_e32 v9, 0xbfb8aa3b, v9
	v_exp_f32_e32 v8, v8
	v_add_f32_e32 v4, 1.0, v4
	v_add_f32_e32 v19, 1.0, v11
	v_rcp_f32_e32 v11, v3
	v_exp_f32_e32 v9, v9
	v_add_f32_e32 v5, 1.0, v5
	v_rcp_f32_e32 v12, v4
	v_add_f32_e32 v6, 1.0, v6
	v_rcp_f32_e32 v13, v5
	v_add_f32_e32 v7, 1.0, v7
	v_rcp_f32_e32 v14, v6
	v_add_f32_e32 v8, 1.0, v8
	v_rcp_f32_e32 v15, v7
	v_add_f32_e32 v9, 1.0, v9
	v_rcp_f32_e32 v16, v8
	v_rcp_f32_e32 v17, v9
	v_rcp_f32_e32 v18, v18
	v_rcp_f32_e32 v19, v19
	s_waitcnt vmcnt(4)
	v_sub_f32_e32 v0, v91, v90
	v_mul_f32_e32 v0, 0x3fb8aa3b, v0
	v_exp_f32_e32 v0, v0
	s_nop 0
	v_add_f32_e32 v0, 1.0, v0
	v_rcp_f32_e32 v1, v0
	s_nop 0
	v_sub_f32_e32 v0, 1.0, v1
	v_fma_f32 v2, v0, v10, v1
	v_log_f32_e32 v2, v2
	v_fma_f32 v3, v0, v11, v1
	v_fma_f32 v4, v0, v12, v1
	v_log_f32_e32 v3, v3
	v_fma_f32 v28, v2, s30, 0
	v_mul_f32_e32 v2, 0xbfb8aa3b, v20
	v_exp_f32_e32 v2, v2
	v_fma_f32 v5, v0, v13, v1
	v_log_f32_e32 v4, v4
	v_fma_f32 v6, v0, v14, v1
	v_add_f32_e32 v2, 1.0, v2
	v_rcp_f32_e32 v20, v2
	s_waitcnt lgkmcnt(4)
	v_lshlrev_b32_e32 v2, 16, v21
	v_log_f32_e32 v5, v5
	v_mul_f32_e32 v2, 0xbfb8aa3b, v2
	v_fma_f32 v7, v0, v15, v1
	v_log_f32_e32 v6, v6
	v_exp_f32_e32 v2, v2
	v_fma_f32 v8, v0, v16, v1
	v_log_f32_e32 v7, v7
	v_fmamk_f32 v29, v3, 0x3f317218, v28
	v_fma_f32 v9, v0, v17, v1
	v_log_f32_e32 v8, v8
	v_fmamk_f32 v30, v4, 0x3f317218, v29
	v_log_f32_e32 v9, v9
	v_fmamk_f32 v31, v5, 0x3f317218, v30
	v_fma_f32 v3, v0, v18, v1
	v_fmamk_f32 v48, v6, 0x3f317218, v31
	v_log_f32_e32 v3, v3
	v_fma_f32 v4, v0, v19, v1
	v_add_f32_e32 v2, 1.0, v2
	v_fmamk_f32 v67, v7, 0x3f317218, v48
	v_log_f32_e32 v4, v4
	v_rcp_f32_e32 v21, v2
	v_fmamk_f32 v68, v8, 0x3f317218, v67
	v_fmamk_f32 v69, v9, 0x3f317218, v68
	v_fma_f32 v5, v0, v20, v1
	v_fmamk_f32 v70, v3, 0x3f317218, v69
	s_waitcnt lgkmcnt(3)
	v_lshlrev_b32_e32 v3, 16, v22
	v_log_f32_e32 v5, v5
	v_fmamk_f32 v71, v4, 0x3f317218, v70
	v_fma_f32 v2, v0, v21, v1
	v_mul_f32_e32 v3, 0xbfb8aa3b, v3
	s_waitcnt lgkmcnt(2)
	v_lshlrev_b32_e32 v4, 16, v23
	v_log_f32_e32 v2, v2
	v_exp_f32_e32 v3, v3
	v_mul_f32_e32 v4, 0xbfb8aa3b, v4
	v_exp_f32_e32 v4, v4
	v_fmamk_f32 v72, v5, 0x3f317218, v71
	v_fmamk_f32 v73, v2, 0x3f317218, v72
	v_add_f32_e32 v2, 1.0, v3
	v_rcp_f32_e32 v22, v2
	v_add_f32_e32 v2, 1.0, v4
	v_rcp_f32_e32 v23, v2
	s_waitcnt lgkmcnt(1)
	v_lshlrev_b32_e32 v2, 16, v24
	v_mul_f32_e32 v2, 0xbfb8aa3b, v2
	v_exp_f32_e32 v2, v2
	v_fma_f32 v3, v0, v22, v1
	v_log_f32_e32 v3, v3
	v_fma_f32 v4, v0, v23, v1
	v_add_f32_e32 v2, 1.0, v2
	v_rcp_f32_e32 v24, v2
	s_waitcnt lgkmcnt(0)
	v_lshlrev_b32_e32 v2, 16, v25
	v_mul_f32_e32 v2, 0xbfb8aa3b, v2
	v_exp_f32_e32 v2, v2
	v_log_f32_e32 v4, v4
	v_fma_f32 v5, v0, v24, v1
	v_log_f32_e32 v5, v5
	v_add_f32_e32 v2, 1.0, v2
	v_rcp_f32_e32 v25, v2
	v_fmamk_f32 v74, v3, 0x3f317218, v73
	v_fmamk_f32 v75, v4, 0x3f317218, v74
	v_fmamk_f32 v76, v5, 0x3f317218, v75
	v_fmac_f32_e32 v1, v0, v25
	v_log_f32_e32 v1, v1
	ds_read_u16 v2, v63 offset:58368
	ds_read_u16 v3, v63 offset:58640
	ds_read_u16 v4, v63 offset:58912
	ds_read_u16 v5, v63 offset:59184
	ds_read_u16 v6, v63 offset:59456
	ds_read_u16 v7, v63 offset:59728
	ds_read_u16 v8, v63 offset:60000
	ds_read_u16 v9, v63 offset:60272
	ds_read_u16 v26, v63 offset:60544
	ds_read_u16 v27, v63 offset:60816
	ds_read_u16 v77, v63 offset:61088
	ds_read_u16 v78, v63 offset:61360
	ds_read_u16 v79, v63 offset:61632
	ds_read_u16 v80, v63 offset:61904
	ds_read_u16 v81, v63 offset:62176
	ds_read_u16 v82, v63 offset:62448
	v_pk_add_f32 v[10:11], v[10:11], 1.0 op_sel_hi:[1,0] neg_lo:[1,0] neg_hi:[1,0]
	v_pk_add_f32 v[12:13], v[12:13], 1.0 op_sel_hi:[1,0] neg_lo:[1,0] neg_hi:[1,0]
	v_pk_add_f32 v[14:15], v[14:15], 1.0 op_sel_hi:[1,0] neg_lo:[1,0] neg_hi:[1,0]
	v_pk_add_f32 v[16:17], v[16:17], 1.0 op_sel_hi:[1,0] neg_lo:[1,0] neg_hi:[1,0]
	s_waitcnt lgkmcnt(14)
	v_lshl_or_b32 v2, v3, 16, v2
	s_waitcnt lgkmcnt(12)
	v_lshl_or_b32 v3, v5, 16, v4
	s_waitcnt lgkmcnt(10)
	v_lshl_or_b32 v4, v7, 16, v6
	s_waitcnt lgkmcnt(8)
	v_lshl_or_b32 v5, v9, 16, v8
	s_waitcnt lgkmcnt(6)
	v_lshl_or_b32 v6, v27, 16, v26
	v_pk_mul_f32 v[10:11], v[0:1], v[10:11] op_sel_hi:[0,1]
	v_pk_mul_f32 v[12:13], v[0:1], v[12:13] op_sel_hi:[0,1]
	v_pk_mul_f32 v[14:15], v[0:1], v[14:15] op_sel_hi:[0,1]
	v_pk_mul_f32 v[16:17], v[0:1], v[16:17] op_sel_hi:[0,1]
	v_fmamk_f32 v27, v1, 0x3f317218, v76
	v_add_u32_e32 v1, v60, v61
	s_waitcnt lgkmcnt(4)
	v_lshl_or_b32 v7, v78, 16, v77
	s_waitcnt lgkmcnt(2)
	v_lshl_or_b32 v8, v80, 16, v79
	s_waitcnt lgkmcnt(0)
	v_lshl_or_b32 v9, v82, 16, v81
	ds_write_b32 v59, v27 offset:36864
	ds_write_b128 v1, v[2:5] offset:18432
	ds_write_b128 v1, v[6:9] offset:18448
	s_waitcnt lgkmcnt(0)
	s_barrier
; #define LAS __attribute__((address_space(3)))
; DI unsigned pk2(float lo, float hi) { return pg8::cvt_pk_bf16(lo, hi); }
; DI void hg_phase_a(const P& p, const bf16_t* PROJ, float* UT, float* DEC, LAS unsigned char* L) {
;     ...
;         float off = 0.f, tot = 0.f;
; #pragma unroll
;         for (int q = 0; q < 4; ++q) { const float v = psum[q * 128 + d]; tot += v; off += (q < part) ? v : 0.f; }
;         { float ke[16];
; #pragma unroll
;           for (int i = 0; i < 16; ++i) ke[i] = kk[i] * __expf(tot - (off + G[i]));
;           u32x4 a, c; a.x = pk2(ke[0], ke[1]); a.y = pk2(ke[2], ke[3]); a.z = pk2(ke[4], ke[5]); a.w = pk2(ke[6], ke[7]);
;           c.x = pk2(ke[8], ke[9]); c.y = pk2(ke[10], ke[11]); c.z = pk2(ke[12], ke[13]); c.w = pk2(ke[14], ke[15]);
;           *(LAS u32x4*)(kendT + d * 144 + part * 32) = a; *(LAS u32x4*)(kendT + d * 144 + part * 32 + 16) = c; }
;         if (part == 0) DEC[(size_t)ch * 128 + d] = __expf(tot);
	ds_read2st64_b32 v[2:3], v62 offset0:144 offset1:146
	ds_read2st64_b32 v[8:9], v62 offset0:148 offset1:150
	v_pk_add_f32 v[4:5], v[18:19], 1.0 op_sel_hi:[1,0] neg_lo:[1,0] neg_hi:[1,0]
	v_pk_add_f32 v[6:7], v[20:21], 1.0 op_sel_hi:[1,0] neg_lo:[1,0] neg_hi:[1,0]
	v_pk_mul_f32 v[4:5], v[0:1], v[4:5] op_sel_hi:[0,1]
	v_pk_mul_f32 v[6:7], v[0:1], v[6:7] op_sel_hi:[0,1]
	s_waitcnt lgkmcnt(1)
	v_add_f32_e32 v1, 0, v2
	v_cndmask_b32_e64 v2, 0, v1, s[6:7]
	v_add_f32_e32 v1, v1, v3
	v_cndmask_b32_e64 v3, 0, v3, s[8:9]
	v_add_f32_e32 v2, v2, v3
	s_waitcnt lgkmcnt(0)
	v_add_f32_e32 v26, v1, v8
	v_cndmask_b32_e64 v1, 0, v8, s[10:11]
	v_add_f32_e32 v1, v2, v1
	v_cndmask_b32_e64 v2, 0, v9, s[12:13]
	v_add_f32_e32 v19, v1, v2
	v_mov_b32_e32 v18, v9
	v_add_f32_e32 v1, v28, v19
	v_pk_add_f32 v[2:3], v[26:27], v[18:19]
	v_pk_add_f32 v[22:23], v[22:23], 1.0 op_sel_hi:[1,0] neg_lo:[1,0] neg_hi:[1,0]
	v_sub_f32_e32 v1, v2, v1
	v_mul_f32_e32 v1, 0x3fb8aa3b, v1
	v_exp_f32_e32 v8, v1
	v_add_f32_e32 v1, v29, v19
	v_sub_f32_e32 v1, v2, v1
	v_mul_f32_e32 v1, 0x3fb8aa3b, v1
	v_exp_f32_e32 v9, v1
	v_add_f32_e32 v1, v30, v19
	v_sub_f32_e32 v1, v2, v1
	v_mul_f32_e32 v1, 0x3fb8aa3b, v1
	v_exp_f32_e32 v20, v1
	v_add_f32_e32 v1, v31, v19
	v_sub_f32_e32 v1, v2, v1
	v_mul_f32_e32 v1, 0x3fb8aa3b, v1
	v_exp_f32_e32 v21, v1
	v_pk_mul_f32 v[22:23], v[0:1], v[22:23] op_sel_hi:[0,1]
	v_add_f32_e32 v1, v48, v19
	v_sub_f32_e32 v1, v2, v1
	v_mul_f32_e32 v1, 0x3fb8aa3b, v1
	v_pk_mul_f32 v[8:9], v[10:11], v[8:9]
	v_pk_mul_f32 v[10:11], v[12:13], v[20:21]
	v_exp_f32_e32 v12, v1
	v_add_f32_e32 v1, v67, v19
	v_sub_f32_e32 v1, v2, v1
	v_mul_f32_e32 v1, 0x3fb8aa3b, v1
	v_exp_f32_e32 v13, v1
	v_add_f32_e32 v1, v68, v19
	v_sub_f32_e32 v1, v2, v1
	v_mul_f32_e32 v1, 0x3fb8aa3b, v1
	v_exp_f32_e32 v20, v1
	v_add_f32_e32 v1, v69, v19
	v_sub_f32_e32 v1, v2, v1
	v_mul_f32_e32 v1, 0x3fb8aa3b, v1
	v_exp_f32_e32 v21, v1
	v_add_f32_e32 v1, v70, v19
	v_sub_f32_e32 v1, v2, v1
	v_mul_f32_e32 v1, 0x3fb8aa3b, v1
	v_exp_f32_e32 v26, v1
	v_add_f32_e32 v1, v71, v19
	v_sub_f32_e32 v1, v2, v1
	v_mul_f32_e32 v1, 0x3fb8aa3b, v1
	v_exp_f32_e32 v27, v1
	v_add_f32_e32 v1, v72, v19
	v_sub_f32_e32 v1, v2, v1
	v_mul_f32_e32 v1, 0x3fb8aa3b, v1
	v_exp_f32_e32 v28, v1
	v_add_f32_e32 v1, v73, v19
	v_sub_f32_e32 v1, v2, v1
	v_mul_f32_e32 v1, 0x3fb8aa3b, v1
	v_exp_f32_e32 v29, v1
	v_add_f32_e32 v1, v74, v19
	v_sub_f32_e32 v1, v2, v1
	v_mul_f32_e32 v1, 0x3fb8aa3b, v1
	v_pk_mul_f32 v[12:13], v[14:15], v[12:13]
	v_pk_mul_f32 v[14:15], v[16:17], v[20:21]
	v_pk_mul_f32 v[16:17], v[4:5], v[26:27]
	v_exp_f32_e32 v4, v1
	v_add_f32_e32 v1, v75, v19
	v_sub_f32_e32 v1, v2, v1
	v_mul_f32_e32 v1, 0x3fb8aa3b, v1
	v_exp_f32_e32 v5, v1
	v_add_f32_e32 v1, v76, v19
	v_sub_f32_e32 v1, v2, v1
	v_mul_f32_e32 v1, 0x3fb8aa3b, v1
	v_pk_mul_f32 v[20:21], v[6:7], v[28:29]
	v_exp_f32_e32 v6, v1
	v_sub_f32_e32 v1, v2, v3
	v_mul_f32_e32 v1, 0x3fb8aa3b, v1
	v_exp_f32_e32 v7, v1
	v_pk_mul_f32 v[18:19], v[22:23], v[4:5]
	v_pk_add_f32 v[4:5], v[24:25], 1.0 op_sel_hi:[1,0] neg_lo:[1,0] neg_hi:[1,0]
	s_nop 0
	v_pk_mul_f32 v[0:1], v[0:1], v[4:5] op_sel_hi:[0,1]
	v_pk_mul_f32 v[0:1], v[0:1], v[6:7]
	v_cvt_pk_bf16_f32 v4, v8, v9
	v_cvt_pk_bf16_f32 v5, v10, v11
	v_cvt_pk_bf16_f32 v6, v12, v13
	v_cvt_pk_bf16_f32 v7, v14, v15
	v_cvt_pk_bf16_f32 v8, v16, v17
	v_cvt_pk_bf16_f32 v9, v20, v21
	v_cvt_pk_bf16_f32 v10, v18, v19
	v_cvt_pk_bf16_f32 v11, v0, v1
	ds_write_b128 v64, v[4:7]
	ds_write_b128 v64, v[8:11] offset:16
	s_and_saveexec_b64 s[20:21], s[4:5]
	s_cbranch_execz .LBB0_284
	v_mul_f32_e32 v0, 0x3fb8aa3b, v2
	v_exp_f32_e32 v2, v0
	s_lshl_b64 s[36:37], s[18:19], 9
	v_lshl_add_u64 v[0:1], v[52:53], 0, s[36:37]
	global_store_dword v[0:1], v2, off
	s_branch .LBB0_284

; DI void hg_gates(const LAS unsigned char* rawf, const float* lbl, int part, int hh, int d, float (&G)[16], float (&kk)[16]) {
;     const float l0 = lbl[hh * 128 + d], l1 = lbl[1024 + hh * 128 + d]; const float lb = __builtin_amdgcn_rcpf(1.f + __expf(l1 - l0));
; DI void hg_phase_c(const P& p, const bf16_t* PROJ, const bf16_t* ST, bf16_t* Y, LAS unsigned char* L, unsigned* qcnt) {
;     ...
;     while (ch < 2048) {
;         const int bh = ch >> 6, n = ch & 63, b = bh >> 3, hh = bh & 7;
;         if (tid == 0) qs[par ^ 1] = __hip_atomic_fetch_add(qcnt, 1u, __ATOMIC_RELAXED, __HIP_MEMORY_SCOPE_AGENT);
;         __syncthreads();
;         const int nxt = (int)qs[par ^ 1];
;         hg_raw_store(rawf, tid, rf); hg_raw_store(rawv, tid, rv); hg_raw_store(rawq, tid, rq);
;         if (nxt < 2048) { hg_raw_load(PROJ, nxt, 4096, roff, rf); hg_raw_load(PROJ, nxt, 5120, roff, rv); hg_raw_load(PROJ, nxt, 3072, roff, rq); }
.LBB0_428:
	s_or_b64 exec, exec, s[50:51]
	s_lshl_b32 s50, s95, 2
	s_add_i32 s50, s50, 0
	s_add_i32 s50, s50, 0x220a0
	v_mov_b32_e32 v0, s50
	s_waitcnt lgkmcnt(0)
	s_barrier
	ds_read_b32 v0, v0
	s_waitcnt vmcnt(5)
	ds_write_b128 v173, v[48:51]
	s_waitcnt vmcnt(3)
	ds_write_b128 v173, v[56:59] offset:8704
	ds_write_b128 v181, v[52:55]
	s_waitcnt vmcnt(2)
	ds_write_b128 v181, v[60:63] offset:8704
	s_waitcnt vmcnt(1)
	ds_write_b128 v182, v[64:67]
	s_waitcnt vmcnt(0)
	ds_write_b128 v182, v[68:71] offset:8704
	s_waitcnt lgkmcnt(6)
	v_cmp_lt_i32_e64 s[50:51], s85, v0
	v_readfirstlane_b32 s96, v0
	s_and_b64 vcc, exec, s[50:51]
	s_lshl_b32 s62, s76, 1
	s_and_b32 s62, s62, 0x380
	v_or_b32_e32 v212, s62, v172
	v_lshlrev_b32_e32 v212, 2, v212
	s_add_u32 s100, s52, 0x1000
	s_addc_u32 s101, s53, 0
	global_load_dword v210, v212, s[52:53]
	global_load_dword v211, v212, s[100:101]
	s_cbranch_vccnz .Lhgc_nopf
	s_ashr_i32 s78, s96, 9
	s_ashr_i32 s79, s78, 31
	s_lshl_b32 s62, s96, 6
	s_lshl_b64 s[78:79], s[78:79], 12
	s_and_b32 s62, s62, 0xfc0
	s_or_b32 s62, s78, s62
	s_mul_i32 s77, s79, 0x3800
	s_mul_hi_u32 s78, s62, 0x3800
	s_add_i32 s78, s78, s77
	s_mulk_i32 s62, 0x3800
	s_add_u32 s62, s64, s62
	s_addc_u32 s77, s65, s78
	s_lshl_b32 s78, s96, 2
	s_and_b32 s78, s78, 0x700
	s_add_u32 s78, s62, s78
	s_addc_u32 s79, s77, 0
	v_lshl_add_u64 v[0:1], v[152:153], 1, s[78:79]
	v_add_co_u32_e32 v2, vcc, s89, v0
	s_nop 1
	v_addc_co_u32_e32 v3, vcc, 0, v1, vcc
	v_add_co_u32_e32 v4, vcc, 0x72000, v0
	s_nop 1
	v_addc_co_u32_e32 v5, vcc, 0, v1, vcc
	global_load_dwordx4 v[48:51], v[2:3], off
	global_load_dwordx4 v[52:55], v[2:3], off offset:2048
	global_load_dwordx4 v[56:59], v[4:5], off
	global_load_dwordx4 v[60:63], v[4:5], off offset:2048
	v_add_co_u32_e32 v2, vcc, 0x1000, v0
	s_nop 1
	v_addc_co_u32_e32 v3, vcc, 0, v1, vcc
	v_add_co_u32_e32 v0, vcc, 0x71000, v0
	s_nop 1
	v_addc_co_u32_e32 v1, vcc, 0, v1, vcc
	global_load_dwordx4 v[64:67], v[2:3], off offset:2048
	global_load_dwordx4 v[68:71], v[0:1], off offset:2048
	s_branch .LBB0_430

; #define LAS __attribute__((address_space(3)))
; DI float bf2f(unsigned v) { return __uint_as_float(v << 16); }
; DI void hg_gates(const LAS unsigned char* rawf, const float* lbl, int part, int hh, int d, float (&G)[16], float (&kk)[16]) {
;     const float l0 = lbl[hh * 128 + d], l1 = lbl[1024 + hh * 128 + d]; const float lb = __builtin_amdgcn_rcpf(1.f + __expf(l1 - l0));
;     float run = 0.f;
; #pragma unroll
;     for (int i = 0; i < 16; ++i) {
;         const float fl = bf2f(*(const LAS bf16_t*)(rawf + (16 * part + i) * 272 + d * 2));
;         const float sig = __builtin_amdgcn_rcpf(1.f + __expf(-fl)); const float f = lb + (1.f - lb) * sig;
;         kk[i] = (1.f - lb) * (1.f - sig); run += __builtin_amdgcn_logf(f) * 0.69314718056f; G[i] = run;
;     }
; DI void hg_phase_c(const P& p, const bf16_t* PROJ, const bf16_t* ST, bf16_t* Y, LAS unsigned char* L, unsigned* qcnt) {
;     ...
;         const int dt = w & 3, tt = w >> 2;
;         bf16x8 stf[8];
;         { const bf16_t* STc = ST + (size_t)ch * 16384 + (32 * dt + r) * 128 + 8 * lh;
; #pragma unroll
;           for (int ks = 0; ks < 8; ++ks) stf[ks] = *(const bf16x8*)(STc + 16 * ks); }
;         const size_t trow = (size_t)b * SEQ + n * 64 + 32 * tt + r;
;         u32x2 ggv[4]; f32x4 ogv[4];
; #pragma unroll
;         for (int g4 = 0; g4 < 4; ++g4) { const int dv0 = 32 * dt + 8 * g4 + 4 * lh; ggv[g4] = *(const u32x2*)(PROJ + trow * PIN + 6144 + hh * 128 + dv0); ogv[g4] = *(const f32x4*)(p.hg_out_norm + hh * 128 + dv0); }
;         float G[16], kk[16];
;         hg_gates(rawf, p.lb_logits, part, hh, d, G, kk);
.LBB0_430:
	s_lshl_b32 s62, s76, 1
	s_and_b32 s80, s62, 0x380
	v_or_b32_e32 v0, s80, v172
	v_lshlrev_b32_e32 v0, 2, v0
	v_mov_b32_e32 v1, v155
	v_lshl_add_u64 v[2:3], s[52:53], 0, v[0:1]
	s_waitcnt lgkmcnt(0)
	s_barrier
	v_add_co_u32_e32 v0, vcc, s90, v2
	s_ashr_i32 s82, s76, 9
	s_nop 0
	v_addc_co_u32_e32 v1, vcc, 0, v3, vcc
	s_ashr_i32 s77, s76, 31
	s_lshl_b32 s62, s76, 6
	s_lshl_b64 s[76:77], s[76:77], 15
	s_ashr_i32 s83, s82, 31
	s_and_b32 s97, s62, 0xfc0
	v_lshl_add_u64 v[2:3], v[156:157], 0, s[76:77]
	s_lshl_b64 s[76:77], s[82:83], 12
	s_or_b32 s76, s76, s97
	v_mov_b64_e32 v[0:1], s[64:65]
	s_mov_b32 s81, s63
	s_lshl_b32 s62, s80, 1
	s_lshl_b32 s80, s80, 2
	v_lshl_add_u64 v[168:169], s[76:77], 0, v[158:159]
	ds_read_u16 v6, v183 offset:57344
	ds_read_u16 v7, v183 offset:57616
	ds_read_u16 v8, v183 offset:57888
	ds_read_u16 v9, v183 offset:58160
	ds_read_u16 v10, v183 offset:58432
	ds_read_u16 v12, v183 offset:58704
	ds_read_u16 v13, v183 offset:58976
	ds_read_u16 v14, v183 offset:59248
	global_load_dwordx4 v[116:119], v[2:3], off
	global_load_dwordx4 v[112:115], v[2:3], off offset:32
	global_load_dwordx4 v[108:111], v[2:3], off offset:64
	global_load_dwordx4 v[104:107], v[2:3], off offset:96
	global_load_dwordx4 v[100:103], v[2:3], off offset:128
	global_load_dwordx4 v[96:99], v[2:3], off offset:160
	global_load_dwordx4 v[92:95], v[2:3], off offset:192
	global_load_dwordx4 v[88:91], v[2:3], off offset:224
	v_lshl_add_u64 v[2:3], v[160:161], 0, s[80:81]
	v_mad_u64_u32 v[0:1], s[76:77], v168, s88, v[0:1]
	global_load_dwordx4 v[84:87], v[2:3], off
	global_load_dwordx4 v[80:83], v[2:3], off offset:32
	global_load_dwordx4 v[76:79], v[2:3], off offset:64
	global_load_dwordx4 v[72:75], v[2:3], off offset:96
	s_waitcnt lgkmcnt(7)
	v_lshlrev_b32_e32 v3, 16, v6
	v_mov_b32_e32 v2, v1
	v_mul_f32_e32 v1, 0xbfb8aa3b, v3
	v_mad_u64_u32 v[2:3], s[76:77], v169, s88, v[2:3]
	s_waitcnt lgkmcnt(6)
	v_lshlrev_b32_e32 v6, 16, v7
	s_waitcnt lgkmcnt(5)
	v_lshlrev_b32_e32 v7, 16, v8
	s_waitcnt lgkmcnt(4)
	v_lshlrev_b32_e32 v8, 16, v9
	v_exp_f32_e32 v9, v1
	v_mov_b32_e32 v1, v2
	v_lshl_add_u64 v[0:1], v[0:1], 0, s[62:63]
	s_mov_b64 s[78:79], 0x3000
	v_mul_f32_e32 v6, 0xbfb8aa3b, v6
	v_lshl_add_u64 v[0:1], v[0:1], 0, v[154:155]
	v_exp_f32_e32 v6, v6
	v_lshl_add_u64 v[2:3], v[0:1], 0, s[78:79]
	v_add_co_u32_e32 v0, vcc, s91, v0
	v_mul_f32_e32 v7, 0xbfb8aa3b, v7
	s_nop 0
	v_addc_co_u32_e32 v1, vcc, 0, v1, vcc
	v_mul_f32_e32 v8, 0xbfb8aa3b, v8
	v_exp_f32_e32 v7, v7
	global_load_dwordx2 v[170:171], v[0:1], off
	global_load_dwordx2 v[166:167], v[2:3], off offset:16
	global_load_dwordx2 v[164:165], v[2:3], off offset:32
	global_load_dwordx2 v[162:163], v[2:3], off offset:48
	v_exp_f32_e32 v15, v8
	v_add_f32_e32 v8, 1.0, v9
	v_add_f32_e32 v6, 1.0, v6
	v_rcp_f32_e32 v0, v8
	v_rcp_f32_e32 v1, v6
	v_add_f32_e32 v7, 1.0, v7
	ds_read_u16 v16, v183 offset:59520
	ds_read_u16 v17, v183 offset:59792
	ds_read_u16 v18, v183 offset:60064
	ds_read_u16 v19, v183 offset:60336
	ds_read_u16 v23, v183 offset:60608
	ds_read_u16 v26, v183 offset:60880
	ds_read_u16 v29, v183 offset:61152
	ds_read_u16 v32, v183 offset:61424
	v_sub_f32_e32 v3, 1.0, v0
	s_waitcnt lgkmcnt(7)
	v_lshlrev_b32_e32 v16, 16, v16
	v_mul_f32_e32 v16, 0xbfb8aa3b, v16
	v_exp_f32_e32 v16, v16
	s_andn2_b64 vcc, exec, s[66:67]
	s_waitcnt vmcnt(22)
	v_sub_f32_e32 v4, v211, v210
	v_mul_f32_e32 v4, 0x3fb8aa3b, v4
	v_exp_f32_e32 v4, v4
	s_nop 0
	v_add_f32_e32 v2, 1.0, v4
	v_rcp_f32_e32 v22, v2
	v_rcp_f32_e32 v2, v7
	v_sub_f32_e32 v4, 1.0, v1
	v_sub_f32_e32 v31, 1.0, v22
	v_fma_f32 v0, v31, v0, v22
	v_fma_f32 v1, v31, v1, v22
	v_log_f32_e32 v0, v0
	v_log_f32_e32 v1, v1
	v_mul_f32_e32 v8, v31, v3
	v_fma_f32 v3, v31, v2, v22
	v_log_f32_e32 v3, v3
	v_fma_f32 v11, v0, s92, 0
	v_fmamk_f32 v9, v1, 0x3f317218, v11
	v_add_f32_e32 v0, 1.0, v15
	v_sub_f32_e32 v1, 1.0, v2
	v_lshlrev_b32_e32 v2, 16, v10
	v_rcp_f32_e32 v0, v0
	v_mul_f32_e32 v2, 0xbfb8aa3b, v2
	v_fmamk_f32 v7, v3, 0x3f317218, v9
	v_exp_f32_e32 v3, v2
	v_mul_f32_e32 v6, v31, v4
	v_mul_f32_e32 v4, v31, v1
	v_fma_f32 v1, v31, v0, v22
	v_sub_f32_e32 v0, 1.0, v0
	v_mul_f32_e32 v2, v31, v0
	v_log_f32_e32 v0, v1
	v_add_f32_e32 v1, 1.0, v3
	v_rcp_f32_e32 v1, v1
	v_lshlrev_b32_e32 v3, 16, v12
	v_mul_f32_e32 v3, 0xbfb8aa3b, v3
	v_exp_f32_e32 v3, v3
	v_fmamk_f32 v5, v0, 0x3f317218, v7
	v_fma_f32 v0, v31, v1, v22
	v_log_f32_e32 v0, v0
	v_add_f32_e32 v3, 1.0, v3
	v_rcp_f32_e32 v10, v3
	v_sub_f32_e32 v1, 1.0, v1
	v_fmamk_f32 v3, v0, 0x3f317218, v5
	v_lshlrev_b32_e32 v0, 16, v13
	v_mul_f32_e32 v0, 0xbfb8aa3b, v0
	v_exp_f32_e32 v13, v0
	v_fma_f32 v12, v31, v10, v22
	v_sub_f32_e32 v0, 1.0, v10
	v_log_f32_e32 v10, v12
	v_add_f32_e32 v12, 1.0, v13
	v_lshlrev_b32_e32 v13, 16, v14
	v_rcp_f32_e32 v12, v12
	v_mul_f32_e32 v13, 0xbfb8aa3b, v13
	v_exp_f32_e32 v14, v13
	v_fmamk_f32 v13, v10, 0x3f317218, v3
	v_fma_f32 v10, v31, v12, v22
	v_log_f32_e32 v15, v10
	v_add_f32_e32 v10, 1.0, v14
	v_rcp_f32_e32 v14, v10
	v_sub_f32_e32 v10, 1.0, v12
	v_fmamk_f32 v12, v15, 0x3f317218, v13
	v_mul_f32_e32 v1, v31, v1
	v_fma_f32 v15, v31, v14, v22
	v_sub_f32_e32 v14, 1.0, v14
	v_mul_f32_e32 v27, v31, v14
	v_log_f32_e32 v14, v15
	v_add_f32_e32 v15, 1.0, v16
	v_rcp_f32_e32 v15, v15
	s_waitcnt lgkmcnt(6)
	v_lshlrev_b32_e32 v16, 16, v17
	v_mul_f32_e32 v16, 0xbfb8aa3b, v16
	v_exp_f32_e32 v16, v16
	v_fmamk_f32 v30, v14, 0x3f317218, v12
	v_fma_f32 v14, v31, v15, v22
	v_sub_f32_e32 v15, 1.0, v15
	v_mul_f32_e32 v24, v31, v15
	s_waitcnt lgkmcnt(5)
	v_lshlrev_b32_e32 v15, 16, v18
	v_add_f32_e32 v16, 1.0, v16
	v_mul_f32_e32 v15, 0xbfb8aa3b, v15
	v_log_f32_e32 v14, v14
	v_rcp_f32_e32 v16, v16
	v_exp_f32_e32 v15, v15
	s_waitcnt lgkmcnt(2)
; #define LAS __attribute__((address_space(3)))
; DI float bf2f(unsigned v) { return __uint_as_float(v << 16); }
; DI void hg_gates(const LAS unsigned char* rawf, const float* lbl, int part, int hh, int d, float (&G)[16], float (&kk)[16]) {
;     const float l0 = lbl[hh * 128 + d], l1 = lbl[1024 + hh * 128 + d]; const float lb = __builtin_amdgcn_rcpf(1.f + __expf(l1 - l0));
;     float run = 0.f;
; #pragma unroll
;     for (int i = 0; i < 16; ++i) {
;         const float fl = bf2f(*(const LAS bf16_t*)(rawf + (16 * part + i) * 272 + d * 2));
;         const float sig = __builtin_amdgcn_rcpf(1.f + __expf(-fl)); const float f = lb + (1.f - lb) * sig;
;         kk[i] = (1.f - lb) * (1.f - sig); run += __builtin_amdgcn_logf(f) * 0.69314718056f; G[i] = run;
;     }
; DI void hg_phase_c(const P& p, const bf16_t* PROJ, const bf16_t* ST, bf16_t* Y, LAS unsigned char* L, unsigned* qcnt) {
;     ...
;         float G[16], kk[16];
;         hg_gates(rawf, p.lb_logits, part, hh, d, G, kk);
;         psum[part * 128 + d] = G[15];
;         { u32x4 a, c; hg_col16(rawv, part, d, a, c);
;           u32x2 t2; t2.x = a.x; t2.y = a.y; *(LAS u32x2*)(vT + d * 136 + part * 32) = t2; t2.x = a.z; t2.y = a.w; *(LAS u32x2*)(vT + d * 136 + part * 32 + 8) = t2;
;           t2.x = c.x; t2.y = c.y; *(LAS u32x2*)(vT + d * 136 + part * 32 + 16) = t2; t2.x = c.z; t2.y = c.w; *(LAS u32x2*)(vT + d * 136 + part * 32 + 24) = t2; }
;         float qs[16];
; #pragma unroll
;         for (int i = 0; i < 16; ++i) { const float ql = bf2f(*(const LAS bf16_t*)(rawq + (16 * part + i) * 272 + d * 2)); qs[i] = ql * __builtin_amdgcn_rcpf(1.f + __expf(-ql)); }
;         __syncthreads();
	v_lshlrev_b32_e32 v17, 16, v26
	v_fmamk_f32 v28, v14, 0x3f317218, v30
	v_fma_f32 v14, v31, v16, v22
	v_sub_f32_e32 v16, 1.0, v16
	v_add_f32_e32 v15, 1.0, v15
	v_mul_f32_e32 v20, v31, v16
	v_log_f32_e32 v14, v14
	v_rcp_f32_e32 v15, v15
	v_lshlrev_b32_e32 v16, 16, v19
	v_mul_f32_e32 v16, 0xbfb8aa3b, v16
	v_exp_f32_e32 v16, v16
	v_fmamk_f32 v25, v14, 0x3f317218, v28
	v_fma_f32 v14, v31, v15, v22
	v_sub_f32_e32 v15, 1.0, v15
	v_mul_f32_e32 v18, v31, v15
	v_lshlrev_b32_e32 v15, 16, v23
	v_add_f32_e32 v16, 1.0, v16
	v_mul_f32_e32 v15, 0xbfb8aa3b, v15
	v_log_f32_e32 v14, v14
	v_rcp_f32_e32 v16, v16
	v_exp_f32_e32 v15, v15
	v_mul_f32_e32 v17, 0xbfb8aa3b, v17
	v_fmamk_f32 v21, v14, 0x3f317218, v25
	v_fma_f32 v14, v31, v16, v22
	v_add_f32_e32 v15, 1.0, v15
	v_log_f32_e32 v14, v14
	v_rcp_f32_e32 v15, v15
	v_exp_f32_e32 v17, v17
	v_sub_f32_e32 v16, 1.0, v16
	v_fmamk_f32 v19, v14, 0x3f317218, v21
	v_fma_f32 v14, v31, v15, v22
	v_add_f32_e32 v17, 1.0, v17
	v_log_f32_e32 v14, v14
	v_rcp_f32_e32 v23, v17
	v_sub_f32_e32 v15, 1.0, v15
	v_mul_f32_e32 v0, v31, v0
	v_fmamk_f32 v17, v14, 0x3f317218, v19
	v_fma_f32 v26, v31, v23, v22
	v_sub_f32_e32 v14, 1.0, v23
	s_waitcnt lgkmcnt(1)
	v_lshlrev_b32_e32 v23, 16, v29
	v_mul_f32_e32 v23, 0xbfb8aa3b, v23
	s_waitcnt lgkmcnt(0)
	v_lshlrev_b32_e32 v29, 16, v32
	v_exp_f32_e32 v23, v23
	v_mul_f32_e32 v29, 0xbfb8aa3b, v29
	v_exp_f32_e32 v29, v29
	v_log_f32_e32 v26, v26
	v_add_f32_e32 v23, 1.0, v23
	v_rcp_f32_e32 v23, v23
	v_add_f32_e32 v29, 1.0, v29
	v_rcp_f32_e32 v40, v29
	v_fmamk_f32 v29, v26, 0x3f317218, v17
	v_fma_f32 v26, v31, v23, v22
	v_log_f32_e32 v26, v26
	v_fmac_f32_e32 v22, v31, v40
	v_log_f32_e32 v32, v22
	v_sub_f32_e32 v22, 1.0, v23
	v_fmamk_f32 v26, v26, 0x3f317218, v29
	v_sub_f32_e32 v40, 1.0, v40
	v_fmamk_f32 v23, v32, 0x3f317218, v26
	ds_write_b32 v175, v23 offset:52224
	ds_read_u16 v32, v184
	ds_read_u16 v33, v184 offset:272
	ds_read_u16 v34, v184 offset:544
	ds_read_u16 v35, v184 offset:816
	ds_read_u16 v36, v184 offset:1088
	ds_read_u16 v37, v184 offset:1360
	ds_read_u16 v38, v184 offset:1632
	ds_read_u16 v39, v184 offset:1904
	ds_read_u16 v41, v184 offset:2176
	ds_read_u16 v42, v184 offset:2448
	ds_read_u16 v43, v184 offset:2720
	ds_read_u16 v44, v184 offset:2992
	ds_read_u16 v45, v184 offset:3264
	ds_read_u16 v46, v184 offset:3536
	ds_read_u16 v47, v184 offset:3808
	ds_read_u16 v120, v184 offset:4080
	s_waitcnt lgkmcnt(14)
	v_lshl_or_b32 v32, v33, 16, v32
	s_waitcnt lgkmcnt(12)
	v_lshl_or_b32 v33, v35, 16, v34
	s_waitcnt lgkmcnt(10)
	v_lshl_or_b32 v34, v37, 16, v36
	s_waitcnt lgkmcnt(8)
	v_lshl_or_b32 v35, v39, 16, v38
	s_waitcnt lgkmcnt(6)
	v_lshl_or_b32 v36, v42, 16, v41
	v_add_u32_e32 v41, 0x8800, v185
	s_waitcnt lgkmcnt(4)
	v_lshl_or_b32 v37, v44, 16, v43
	s_waitcnt lgkmcnt(2)
	v_lshl_or_b32 v38, v46, 16, v45
	s_waitcnt lgkmcnt(0)
	v_lshl_or_b32 v39, v120, 16, v47
	ds_write2_b64 v41, v[32:33], v[34:35] offset1:1
	v_add_u32_e32 v32, 0x8810, v185
	ds_write2_b64 v32, v[36:37], v[38:39] offset1:1
	ds_read_u16 v32, v186
	ds_read_u16 v33, v186 offset:272
	ds_read_u16 v34, v186 offset:544
	ds_read_u16 v35, v186 offset:816
	ds_read_u16 v36, v186 offset:1088
	ds_read_u16 v37, v186 offset:1360
	ds_read_u16 v39, v186 offset:1632
	ds_read_u16 v42, v186 offset:1904
	s_waitcnt lgkmcnt(6)
	v_lshlrev_b32_e32 v33, 16, v33
	v_lshlrev_b32_e32 v32, 16, v32
	v_mul_f32_e32 v41, 0xbfb8aa3b, v33
	v_mul_f32_e32 v38, 0xbfb8aa3b, v32
	v_exp_f32_e32 v41, v41
	v_exp_f32_e32 v38, v38
	s_waitcnt lgkmcnt(5)
	v_lshlrev_b32_e32 v34, 16, v34
	v_mul_f32_e32 v43, 0xbfb8aa3b, v34
	v_add_f32_e32 v41, 1.0, v41
	v_add_f32_e32 v38, 1.0, v38
	v_rcp_f32_e32 v41, v41
	v_rcp_f32_e32 v38, v38
	s_waitcnt lgkmcnt(3)
	v_lshlrev_b32_e32 v36, 16, v36
	v_exp_f32_e32 v44, v43
	v_mul_f32_e32 v41, v41, v33
	v_lshlrev_b32_e32 v33, 16, v35
	v_mul_f32_e32 v43, v38, v32
	v_mul_f32_e32 v35, 0xbfb8aa3b, v33
	v_mul_f32_e32 v38, 0xbfb8aa3b, v36
	v_exp_f32_e32 v35, v35
	v_exp_f32_e32 v38, v38
	v_add_f32_e32 v32, 1.0, v44
	v_rcp_f32_e32 v32, v32
	v_add_f32_e32 v35, 1.0, v35
	v_add_f32_e32 v38, 1.0, v38
	v_mul_f32_e32 v10, v31, v10
	v_mul_f32_e32 v16, v31, v16
	v_mul_f32_e32 v15, v31, v15
	v_mul_f32_e32 v14, v31, v14
	v_mul_f32_e32 v22, v31, v22
	v_mul_f32_e32 v31, v31, v40
	v_rcp_f32_e32 v35, v35
	v_rcp_f32_e32 v40, v38
	s_waitcnt lgkmcnt(2)
	v_lshlrev_b32_e32 v37, 16, v37
	v_mul_f32_e32 v38, 0xbfb8aa3b, v37
	v_exp_f32_e32 v44, v38
	v_mul_f32_e32 v38, v32, v34
	s_waitcnt lgkmcnt(1)
	v_lshlrev_b32_e32 v34, 16, v39
	v_mul_f32_e32 v35, v35, v33
	v_mul_f32_e32 v33, v40, v36
	v_mul_f32_e32 v36, 0xbfb8aa3b, v34
	s_waitcnt lgkmcnt(0)
	v_lshlrev_b32_e32 v39, 16, v42
	v_exp_f32_e32 v36, v36
	v_mul_f32_e32 v40, 0xbfb8aa3b, v39
	v_exp_f32_e32 v40, v40
	v_add_f32_e32 v32, 1.0, v44
	v_add_f32_e32 v36, 1.0, v36
	v_rcp_f32_e32 v32, v32
	v_rcp_f32_e32 v36, v36
	v_add_f32_e32 v40, 1.0, v40
	v_rcp_f32_e32 v40, v40
	ds_read_u16 v42, v186 offset:2176
	ds_read_u16 v44, v186 offset:2448
	ds_read_u16 v45, v186 offset:2720
	ds_read_u16 v46, v186 offset:2992
	ds_read_u16 v47, v186 offset:3264
	ds_read_u16 v120, v186 offset:3536
	ds_read_u16 v121, v186 offset:3808
	ds_read_u16 v122, v186 offset:4080
	s_waitcnt lgkmcnt(7)
	v_lshlrev_b32_e32 v42, 16, v42
	v_mul_f32_e32 v123, 0xbfb8aa3b, v42
	v_mul_f32_e32 v124, v32, v37
	v_mul_f32_e32 v125, v36, v34
	s_waitcnt lgkmcnt(6)
	v_lshlrev_b32_e32 v34, 16, v44
	s_waitcnt lgkmcnt(5)
	v_lshlrev_b32_e32 v37, 16, v45
	v_exp_f32_e32 v123, v123
	v_mul_f32_e32 v126, v40, v39
	v_mul_f32_e32 v36, 0xbfb8aa3b, v34
	v_mul_f32_e32 v39, 0xbfb8aa3b, v37
	v_exp_f32_e32 v36, v36
	v_exp_f32_e32 v39, v39
	s_waitcnt lgkmcnt(4)
	v_lshlrev_b32_e32 v40, 16, v46
	v_add_f32_e32 v32, 1.0, v123
	v_mul_f32_e32 v44, 0xbfb8aa3b, v40
	v_rcp_f32_e32 v32, v32
	v_add_f32_e32 v36, 1.0, v36
	v_add_f32_e32 v39, 1.0, v39
	v_exp_f32_e32 v45, v44
	v_rcp_f32_e32 v36, v36
	v_rcp_f32_e32 v39, v39
	v_mul_f32_e32 v44, v32, v42
	v_add_f32_e32 v32, 1.0, v45
	s_waitcnt lgkmcnt(2)
	v_lshlrev_b32_e32 v45, 16, v120
	v_mul_f32_e32 v42, v36, v34
	v_mul_f32_e32 v39, v39, v37
	v_lshlrev_b32_e32 v34, 16, v47
	v_mul_f32_e32 v37, 0xbfb8aa3b, v45
	v_mul_f32_e32 v36, 0xbfb8aa3b, v34
	v_exp_f32_e32 v37, v37
	v_exp_f32_e32 v36, v36
	s_waitcnt lgkmcnt(1)
	v_lshlrev_b32_e32 v120, 16, v121
	v_rcp_f32_e32 v32, v32
	v_add_f32_e32 v37, 1.0, v37
	v_add_f32_e32 v36, 1.0, v36
	v_rcp_f32_e32 v46, v37
	v_mul_f32_e32 v37, 0xbfb8aa3b, v120
	v_rcp_f32_e32 v36, v36
	v_exp_f32_e32 v47, v37
	v_mul_f32_e32 v37, v32, v40
	v_mul_f32_e32 v32, v46, v45
	v_mul_f32_e32 v34, v36, v34
	v_add_f32_e32 v36, 1.0, v47
	v_rcp_f32_e32 v36, v36
	s_waitcnt lgkmcnt(0)
	v_lshlrev_b32_e32 v45, 16, v122
	v_mul_f32_e32 v40, 0xbfb8aa3b, v45
	v_exp_f32_e32 v40, v40
	s_barrier
; #define LAS __attribute__((address_space(3)))
; DI bf16_t f2bf(float x) { return (bf16_t)(pk2(x, 0.f) & 0xffffu); }
; DI void hg_phase_c(const P& p, const bf16_t* PROJ, const bf16_t* ST, bf16_t* Y, LAS unsigned char* L, unsigned* qcnt) {
;     ...
;         float off = 0.f;
; #pragma unroll
;         for (int q = 0; q < 4; ++q) { const float v = psum[q * 128 + d]; off += (q < part) ? v : 0.f; }
; #pragma unroll
;         for (int i = 0; i < 16; ++i) { const float g = off + G[i];
;             *(LAS bf16_t*)(qd + (16 * part + i) * 272 + d * 2) = f2bf(qs[i] * __expf(g));
;             *(LAS bf16_t*)(ki + (16 * part + i) * 272 + d * 2) = f2bf(kk[i] * __expf(-g)); }
;         __syncthreads();
	ds_read2st64_b32 v[46:47], v176 offset0:204 offset1:206
	v_mul_f32_e32 v36, v36, v120
	ds_read2st64_b32 v[120:121], v176 offset0:208 offset1:210
	v_add_f32_e32 v40, 1.0, v40
	v_rcp_f32_e32 v122, v40
	s_waitcnt lgkmcnt(1)
	v_add_f32_e32 v40, 0, v46
	v_cndmask_b32_e64 v40, 0, v40, s[8:9]
	v_cndmask_b32_e64 v46, 0, v47, s[10:11]
	v_add_f32_e32 v40, v40, v46
	s_waitcnt lgkmcnt(0)
	v_cndmask_b32_e64 v46, 0, v120, s[12:13]
	v_add_f32_e32 v40, v40, v46
	v_cndmask_b32_e64 v46, 0, v121, s[14:15]
	v_add_f32_e32 v40, v40, v46
	v_add_f32_e32 v46, v11, v40
	v_mul_f32_e32 v11, 0x3fb8aa3b, v46
	v_exp_f32_e32 v47, v11
	v_mul_f32_e32 v11, v122, v45
	v_mul_f32_e32 v45, 0xbfb8aa3b, v46
	v_exp_f32_e32 v45, v45
	v_add_f32_e32 v9, v9, v40
	v_add_f32_e32 v7, v7, v40
	v_add_f32_e32 v5, v5, v40
	v_mul_f32_e32 v8, v8, v45
	v_cvt_pk_bf16_f32 v8, v8, s0
	ds_write_b16 v187, v8 offset:17408
	v_mul_f32_e32 v8, 0xbfb8aa3b, v9
	v_exp_f32_e32 v8, v8
	v_add_f32_e32 v3, v3, v40
	v_mul_f32_e32 v43, v43, v47
	v_cvt_pk_bf16_f32 v43, v43, s0
	v_mul_f32_e32 v6, v6, v8
	v_cvt_pk_bf16_f32 v6, v6, s0
	ds_write_b16 v187, v6 offset:17680
	v_mul_f32_e32 v6, 0xbfb8aa3b, v7
	v_exp_f32_e32 v6, v6
	ds_write_b16 v187, v43
	v_mul_f32_e32 v43, 0x3fb8aa3b, v9
	v_mul_f32_e32 v8, 0x3fb8aa3b, v7
	v_mul_f32_e32 v4, v4, v6
	v_cvt_pk_bf16_f32 v4, v4, s0
	ds_write_b16 v187, v4 offset:17952
	v_mul_f32_e32 v4, 0xbfb8aa3b, v5
	v_exp_f32_e32 v4, v4
	v_mul_f32_e32 v6, 0x3fb8aa3b, v5
	v_exp_f32_e32 v43, v43
	v_exp_f32_e32 v8, v8
	v_mul_f32_e32 v2, v2, v4
	v_cvt_pk_bf16_f32 v2, v2, s0
	v_mul_f32_e32 v4, 0x3fb8aa3b, v3
	v_exp_f32_e32 v4, v4
	ds_write_b16 v187, v2 offset:18224
	v_mul_f32_e32 v2, 0xbfb8aa3b, v3
	v_exp_f32_e32 v2, v2
	v_mul_f32_e32 v3, v33, v4
	v_cvt_pk_bf16_f32 v3, v3, s0
	ds_write_b16 v187, v3 offset:1088
	v_mul_f32_e32 v1, v1, v2
	v_add_f32_e32 v2, v13, v40
	v_cvt_pk_bf16_f32 v1, v1, s0
	v_mul_f32_e32 v3, 0x3fb8aa3b, v2
	v_exp_f32_e32 v3, v3
	ds_write_b16 v187, v1 offset:18496
	v_mul_f32_e32 v1, 0xbfb8aa3b, v2
	v_exp_f32_e32 v1, v1
	v_mul_f32_e32 v2, v124, v3
	v_cvt_pk_bf16_f32 v2, v2, s0
	ds_write_b16 v187, v2 offset:1360
	v_mul_f32_e32 v0, v0, v1
	v_add_f32_e32 v1, v12, v40
	v_mul_f32_e32 v2, 0x3fb8aa3b, v1
	v_exp_f32_e32 v2, v2
	v_cvt_pk_bf16_f32 v0, v0, s0
	ds_write_b16 v187, v0 offset:18768
	v_mul_f32_e32 v0, 0xbfb8aa3b, v1
	v_mul_f32_e32 v1, v125, v2
	v_cvt_pk_bf16_f32 v1, v1, s0
	v_exp_f32_e32 v0, v0
	ds_write_b16 v187, v1 offset:1632
	v_add_f32_e32 v1, v30, v40
	v_mul_f32_e32 v2, 0x3fb8aa3b, v1
	v_exp_f32_e32 v2, v2
	v_mul_f32_e32 v0, v10, v0
	v_cvt_pk_bf16_f32 v0, v0, s0
	ds_write_b16 v187, v0 offset:19040
	v_mul_f32_e32 v0, 0xbfb8aa3b, v1
	v_mul_f32_e32 v1, v126, v2
	v_cvt_pk_bf16_f32 v1, v1, s0
	v_exp_f32_e32 v0, v0
	ds_write_b16 v187, v1 offset:1904
	v_add_f32_e32 v1, v28, v40
	v_mul_f32_e32 v2, 0x3fb8aa3b, v1
	v_exp_f32_e32 v2, v2
	v_mul_f32_e32 v0, v27, v0
	v_cvt_pk_bf16_f32 v0, v0, s0
	ds_write_b16 v187, v0 offset:19312
	v_mul_f32_e32 v0, 0xbfb8aa3b, v1
	v_mul_f32_e32 v1, v44, v2
	v_cvt_pk_bf16_f32 v1, v1, s0
	v_exp_f32_e32 v0, v0
	ds_write_b16 v187, v1 offset:2176
	v_add_f32_e32 v1, v25, v40
	v_mul_f32_e32 v2, 0x3fb8aa3b, v1
	v_exp_f32_e32 v2, v2
	v_mul_f32_e32 v0, v24, v0
	v_cvt_pk_bf16_f32 v0, v0, s0
	ds_write_b16 v187, v0 offset:19584
	v_mul_f32_e32 v0, 0xbfb8aa3b, v1
	v_mul_f32_e32 v1, v42, v2
	v_cvt_pk_bf16_f32 v1, v1, s0
	v_exp_f32_e32 v0, v0
	ds_write_b16 v187, v1 offset:2448
	v_add_f32_e32 v1, v21, v40
	v_mul_f32_e32 v2, 0x3fb8aa3b, v1
	v_exp_f32_e32 v2, v2
	v_mul_f32_e32 v0, v20, v0
	v_cvt_pk_bf16_f32 v0, v0, s0
	ds_write_b16 v187, v0 offset:19856
	v_mul_f32_e32 v0, 0xbfb8aa3b, v1
	v_mul_f32_e32 v1, v39, v2
	v_exp_f32_e32 v0, v0
	v_cvt_pk_bf16_f32 v1, v1, s0
	ds_write_b16 v187, v1 offset:2720
	v_add_f32_e32 v1, v19, v40
	v_mul_f32_e32 v2, 0x3fb8aa3b, v1
	v_exp_f32_e32 v2, v2
	v_mul_f32_e32 v0, v18, v0
	v_cvt_pk_bf16_f32 v0, v0, s0
	ds_write_b16 v187, v0 offset:20128
	v_mul_f32_e32 v0, 0xbfb8aa3b, v1
	v_exp_f32_e32 v0, v0
	v_mul_f32_e32 v1, v37, v2
	v_cvt_pk_bf16_f32 v1, v1, s0
	ds_write_b16 v187, v1 offset:2992
	v_add_f32_e32 v1, v17, v40
	v_mul_f32_e32 v2, 0x3fb8aa3b, v1
	v_mul_f32_e32 v0, v16, v0
	v_exp_f32_e32 v2, v2
	v_cvt_pk_bf16_f32 v0, v0, s0
	ds_write_b16 v187, v0 offset:20400
	v_mul_f32_e32 v0, 0xbfb8aa3b, v1
	v_exp_f32_e32 v0, v0
	v_mul_f32_e32 v1, v34, v2
	v_cvt_pk_bf16_f32 v1, v1, s0
	ds_write_b16 v187, v1 offset:3264
	v_add_f32_e32 v1, v29, v40
	v_mul_f32_e32 v0, v15, v0
	v_mul_f32_e32 v2, 0x3fb8aa3b, v1
	v_cvt_pk_bf16_f32 v0, v0, s0
	v_exp_f32_e32 v2, v2
	ds_write_b16 v187, v0 offset:20672
	v_mul_f32_e32 v0, 0xbfb8aa3b, v1
	v_exp_f32_e32 v0, v0
	v_mul_f32_e32 v1, v32, v2
	v_cvt_pk_bf16_f32 v1, v1, s0
	ds_write_b16 v187, v1 offset:3536
	v_mul_f32_e32 v0, v14, v0
	v_add_f32_e32 v1, v26, v40
	v_cvt_pk_bf16_f32 v0, v0, s0
	v_mul_f32_e32 v2, 0x3fb8aa3b, v1
	v_exp_f32_e32 v2, v2
	ds_write_b16 v187, v0 offset:20944
	v_mul_f32_e32 v0, 0xbfb8aa3b, v1
	v_exp_f32_e32 v0, v0
	v_mul_f32_e32 v1, v36, v2
	v_cvt_pk_bf16_f32 v1, v1, s0
	ds_write_b16 v187, v1 offset:3808
	v_mul_f32_e32 v0, v22, v0
	v_cvt_pk_bf16_f32 v0, v0, s0
	v_add_f32_e32 v1, v23, v40
	v_mul_f32_e32 v2, 0x3fb8aa3b, v1
	ds_write_b16 v187, v0 offset:21216
	v_mul_f32_e32 v0, 0xbfb8aa3b, v1
	v_exp_f32_e32 v6, v6
	v_exp_f32_e32 v2, v2
	v_exp_f32_e32 v0, v0
	v_mul_f32_e32 v9, v41, v43
	v_mul_f32_e32 v7, v38, v8
	v_mul_f32_e32 v5, v35, v6
	v_mul_f32_e32 v1, v11, v2
	v_mul_f32_e32 v0, v31, v0
	v_cvt_pk_bf16_f32 v9, v9, s0
	v_cvt_pk_bf16_f32 v7, v7, s0
	v_cvt_pk_bf16_f32 v5, v5, s0
	v_cvt_pk_bf16_f32 v1, v1, s0
	v_cvt_pk_bf16_f32 v0, v0, s0
	ds_write_b16 v187, v9 offset:272
	ds_write_b16 v187, v7 offset:544
	ds_write_b16 v187, v5 offset:816
	ds_write_b16 v187, v1 offset:4080
	ds_write_b16 v187, v0 offset:21488
	s_waitcnt lgkmcnt(0)
	s_barrier
; #define LAS __attribute__((address_space(3)))
; #define MFMA32(a, b, c) __builtin_amdgcn_mfma_f32_32x32x16_bf16((a), (b), (c), 0, 0, 0)
; DI int crow(int reg, int h) { return (reg & 3) + 8 * (reg >> 2) + 4 * h; }
; DI void hg_phase_c(const P& p, const bf16_t* PROJ, const bf16_t* ST, bf16_t* Y, LAS unsigned char* L, unsigned* qcnt) {
;     ...
;         bf16x8 qfr[8];
; #pragma unroll
;         for (int ks = 0; ks < 8; ++ks) qfr[ks] = *(const LAS bf16x8*)(qd + (32 * tt + r) * 272 + (16 * ks + 8 * lh) * 2);
;         f32x16 O = zero16();
; #pragma unroll
;         for (int st = 0; st < 2; ++st) {
;             if (st <= tt) {
;                 f32x16 X = zero16();
; #pragma unroll
;                 for (int ks = 0; ks < 8; ++ks) { const bf16x8 a = *(const LAS bf16x8*)(ki + (32 * st + r) * 272 + (16 * ks + 8 * lh) * 2); X = MFMA32(a, qfr[ks], X); }
;                 if (st == tt) {
; #pragma unroll
;                     for (int reg = 0; reg < 16; ++reg) X[reg] = (crow(reg, lh) > r) ? 0.f : X[reg];
;                 }
	ds_read_b128 v[148:151], v188
	ds_read_b128 v[144:147], v188 offset:32
	ds_read_b128 v[140:143], v188 offset:64
	ds_read_b128 v[136:139], v188 offset:96
	ds_read_b128 v[132:135], v188 offset:128
	ds_read_b128 v[128:131], v188 offset:160
	ds_read_b128 v[124:127], v188 offset:192
	ds_read_b128 v[120:123], v188 offset:224
	s_cbranch_vccnz .LBB0_434
	ds_read_b128 v[0:3], v190 offset:17408
	ds_read_b128 v[16:19], v190 offset:17440
	s_andn2_b64 vcc, exec, s[68:69]
	s_waitcnt lgkmcnt(1)
	v_mfma_f32_32x32x16_bf16 v[0:15], v[0:3], v[148:151], 0
	s_waitcnt lgkmcnt(0)
	v_mfma_f32_32x32x16_bf16 v[0:15], v[16:19], v[144:147], v[0:15]
	ds_read_b128 v[16:19], v190 offset:17472
	ds_read_b128 v[20:23], v190 offset:17504
	s_waitcnt lgkmcnt(1)
	v_mfma_f32_32x32x16_bf16 v[0:15], v[16:19], v[140:143], v[0:15]
	s_waitcnt lgkmcnt(0)
	v_mfma_f32_32x32x16_bf16 v[0:15], v[20:23], v[136:139], v[0:15]
	ds_read_b128 v[16:19], v190 offset:17536
	ds_read_b128 v[20:23], v190 offset:17568
	s_waitcnt lgkmcnt(1)
	v_mfma_f32_32x32x16_bf16 v[0:15], v[16:19], v[132:135], v[0:15]
	s_waitcnt lgkmcnt(0)
	v_mfma_f32_32x32x16_bf16 v[0:15], v[20:23], v[128:131], v[0:15]
	ds_read_b128 v[16:19], v190 offset:17600
	ds_read_b128 v[20:23], v190 offset:17632
	s_waitcnt lgkmcnt(1)
	v_mfma_f32_32x32x16_bf16 v[0:15], v[16:19], v[124:127], v[0:15]
	s_waitcnt lgkmcnt(0)
	v_mfma_f32_32x32x16_bf16 v[0:15], v[20:23], v[120:123], v[0:15]
	s_cbranch_vccnz .LBB0_433
	s_nop 10
	v_cndmask_b32_e64 v0, v0, 0, s[16:17]
	v_cndmask_b32_e64 v1, 0, v1, s[18:19]
	v_cndmask_b32_e64 v2, v2, 0, s[20:21]
	v_cndmask_b32_e64 v3, v3, 0, s[22:23]
	v_cndmask_b32_e64 v4, v4, 0, s[24:25]
	v_cndmask_b32_e64 v5, v5, 0, s[26:27]
	v_cndmask_b32_e64 v6, v6, 0, s[28:29]
	v_cndmask_b32_e64 v7, v7, 0, s[30:31]
	v_cndmask_b32_e64 v8, v8, 0, s[34:35]
	v_cndmask_b32_e64 v9, v9, 0, s[36:37]
	v_cndmask_b32_e64 v10, v10, 0, s[38:39]
	v_cndmask_b32_e64 v11, v11, 0, s[40:41]
	v_cndmask_b32_e64 v12, v12, 0, s[42:43]
	v_cndmask_b32_e64 v13, v13, 0, s[44:45]
	v_cndmask_b32_e64 v14, v14, 0, s[46:47]
	v_cndmask_b32_e64 v15, v15, 0, s[48:49]
